# attention FIXM loop: four x+0 partial-sum copies per step folded into their consumers (8 fewer VALU per iteration, bit-identical); with barrier top-gen wait and q/k scale fold
# speedup vs baseline: 1.0075x; 1.0075x over previous
.LBB0_898:
	s_add_i32 s9, s3, -1
	s_min_u32 s9, s9, s2
	s_lshl_b32 s9, s9, 6
	s_waitcnt vmcnt(1)
	ds_write_b128 v142, v[112:115] offset:16384
	s_waitcnt vmcnt(0)
	ds_write_b128 v142, v[116:119] offset:24576
	v_mad_u64_u32 v[64:65], s[18:19], s9, v237, v[132:133]
	global_load_dwordx4 v[120:123], v[64:65], off offset:2048
	global_load_dwordx4 v[124:127], v[136:137], off offset:-128
	ds_read_b128 v[64:67], v144 offset:8192
	ds_read_b128 v[68:71], v144 offset:12288
	ds_read_b128 v[72:75], v141 offset:8192
	ds_read_b128 v[76:79], v141 offset:12288
	v_exp_f32_e32 v151, v48
	v_exp_f32_e32 v152, v49
	s_waitcnt lgkmcnt(3)
	v_mfma_f32_32x32x16_bf16 v[16:31], v[64:67], v[80:83], v[16:31]
	v_exp_f32_e32 v153, v50
	v_exp_f32_e32 v154, v51
	ds_read_b128 v[48:51], v140 offset:8192
	ds_read_b128 v[64:67], v140 offset:12288
	v_exp_f32_e32 v155, v52
	s_waitcnt lgkmcnt(4)
	v_mfma_f32_32x32x16_bf16 v[0:15], v[68:71], v[80:83], v[0:15]
	v_exp_f32_e32 v156, v53
	v_exp_f32_e32 v159, v54
	v_exp_f32_e32 v160, v55
	v_exp_f32_e32 v162, v57
	s_waitcnt lgkmcnt(3)
	v_mfma_f32_32x32x16_bf16 v[16:31], v[72:75], v[84:87], v[16:31]
	ds_read_b128 v[68:71], v139 offset:8192
	ds_read_b128 v[80:83], v139 offset:12288
	v_add_f32_e32 v157, v155, v151
	v_add_f32_e32 v158, v156, v152
	v_add_u32_e32 v164, v143, v145
	ds_read_b128 v[52:55], v164
	ds_read_b128 v[72:75], v164 offset:4096
	v_add_f32_e32 v161, v159, v153
	s_waitcnt lgkmcnt(6)
	v_mfma_f32_32x32x16_bf16 v[0:15], v[76:79], v[84:87], v[0:15]
	v_exp_f32_e32 v77, v56
	v_add_f32_e32 v76, v160, v154
	v_exp_f32_e32 v62, v62
	v_add_u32_e32 v165, v143, v146
	ds_read_b128 v[112:115], v165
	ds_read_b128 v[116:119], v165 offset:4096
	v_cvt_pk_bf16_f32 v56, v151, v152
	s_waitcnt lgkmcnt(7)
	v_mfma_f32_32x32x16_bf16 v[16:31], v[48:51], v[88:91], v[16:31]
	v_exp_f32_e32 v49, v58
	v_exp_f32_e32 v50, v59
	v_add_f32_e32 v48, v77, v157
	v_add_f32_e32 v51, v162, v158
	v_add_f32_e32 v78, v49, v161
	v_add_f32_e32 v76, v50, v76
	s_waitcnt lgkmcnt(6)
	v_mfma_f32_32x32x16_bf16 v[0:15], v[64:67], v[88:91], v[0:15]
	v_exp_f32_e32 v60, v60
	v_add_f32_e32 v151, v62, v78
	v_exp_f32_e32 v61, v61
	v_exp_f32_e32 v63, v63
	v_cvt_pk_bf16_f32 v59, v159, v160
	v_exp_f32_e32 v160, v33
	s_waitcnt lgkmcnt(5)
	v_mfma_f32_32x32x16_bf16 v[16:31], v[68:71], v[92:95], v[16:31]
	v_cvt_pk_bf16_f32 v57, v153, v154
	v_cvt_pk_bf16_f32 v58, v155, v156
	v_add_f32_e32 v48, v60, v48
	v_add_f32_e32 v51, v61, v51
	v_cvt_pk_bf16_f32 v49, v49, v50
	s_waitcnt lgkmcnt(4)
	v_mfma_f32_32x32x16_bf16 v[0:15], v[80:83], v[92:95], v[0:15]
	v_exp_f32_e32 v95, v32
	v_add_f32_e32 v32, v63, v76
	v_add_f32_e32 v163, v160, v51
	v_add_f32_e32 v161, v95, v48
	v_cvt_pk_bf16_f32 v48, v77, v162
	v_cvt_pk_bf16_f32 v51, v62, v63
	s_waitcnt lgkmcnt(3)
	v_mfma_f32_32x32x16_bf16 v[78:93], v[52:55], v[96:99], 0
	v_cvt_pk_bf16_f32 v50, v60, v61
	v_exp_f32_e32 v60, v34
	v_exp_f32_e32 v61, v35
	v_exp_f32_e32 v36, v36
	v_exp_f32_e32 v37, v37
	v_exp_f32_e32 v38, v38
	v_exp_f32_e32 v39, v39
	s_waitcnt lgkmcnt(2)
	v_mfma_f32_32x32x16_bf16 v[62:77], v[72:75], v[96:99], 0
	v_add_u32_e32 v166, v143, v147
	ds_read_b128 v[52:55], v166
	ds_read_b128 v[152:155], v166 offset:4096
	v_add_f32_e32 v151, v60, v151
	v_add_f32_e32 v162, v61, v32
	s_waitcnt lgkmcnt(3)
	v_mfma_f32_32x32x16_bf16 v[78:93], v[112:115], v[100:103], v[78:93]
	v_add_u32_e32 v94, v143, v149
	v_add_f32_e32 v112, v36, v161
	v_add_f32_e32 v113, v37, v163
	v_add_f32_e32 v114, v38, v151
	v_exp_f32_e32 v115, v40
	v_add_f32_e32 v40, v39, v162
	ds_read_b128 v[32:35], v94
	ds_read_b128 v[156:159], v94 offset:4096
	s_waitcnt lgkmcnt(4)
	v_mfma_f32_32x32x16_bf16 v[62:77], v[116:119], v[100:103], v[62:77]
	v_exp_f32_e32 v116, v41
	v_add_f32_e32 v41, v115, v112
	s_min_u32 s9, s3, s2
	s_lshl_b32 s9, s9, 6
	v_add_f32_e32 v112, v116, v113
	s_waitcnt lgkmcnt(3)
	v_mfma_f32_32x32x16_bf16 v[78:93], v[52:55], v[104:107], v[78:93]
	v_cvt_pk_bf16_f32 v54, v36, v37
	v_exp_f32_e32 v37, v42
	v_cvt_pk_bf16_f32 v55, v38, v39
	v_exp_f32_e32 v38, v43
	v_exp_f32_e32 v39, v44
	v_exp_f32_e32 v44, v45
	v_exp_f32_e32 v45, v46
	v_exp_f32_e32 v46, v47
	v_cvt_pk_bf16_f32 v52, v95, v160
	v_cvt_pk_bf16_f32 v53, v60, v61
	v_add_f32_e32 v36, v37, v114
	v_add_f32_e32 v43, v38, v40
	v_add_f32_e32 v40, v39, v41
	v_add_f32_e32 v42, v44, v112
	v_add_f32_e32 v41, v45, v36
	v_add_f32_e32 v43, v46, v43
	v_cvt_pk_bf16_f32 v36, v115, v116
	v_cvt_pk_bf16_f32 v37, v37, v38
	v_cvt_pk_bf16_f32 v38, v39, v44
	v_cvt_pk_bf16_f32 v39, v45, v46
	s_waitcnt lgkmcnt(1)
	v_mfma_f32_32x32x16_bf16 v[78:93], v[32:35], v[108:111], v[78:93]
	s_waitcnt lgkmcnt(0)
	s_barrier
	v_mad_u64_u32 v[32:33], s[18:19], s9, v237, v[132:133]
	global_load_dwordx4 v[112:115], v[32:33], off offset:2048
	global_load_dwordx4 v[116:119], v[136:137], off
	v_add_f32_e64 v32, v40, v42
	v_add_f32_e64 v33, v41, v43
	s_waitcnt vmcnt(3)
	ds_write_b128 v142, v[120:123]
	s_waitcnt vmcnt(2)
	ds_write_b128 v142, v[124:127] offset:8192
	v_mfma_f32_32x32x16_bf16 v[62:77], v[152:155], v[104:107], v[62:77]
	v_add_f32_e32 v32, v32, v33
	v_add_f32_e32 v150, v150, v32
	s_waitcnt lgkmcnt(2)
	v_mfma_f32_32x32x16_bf16 v[62:77], v[156:159], v[108:111], v[62:77]
	ds_read_b128 v[32:35], v144 offset:24576
	ds_read_b128 v[40:43], v144 offset:28672
	ds_read_b128 v[44:47], v141 offset:24576
	ds_read_b128 v[120:123], v141 offset:28672
	v_exp_f32_e32 v60, v78
	s_waitcnt lgkmcnt(3)
	v_mfma_f32_32x32x16_bf16 v[16:31], v[32:35], v[56:59], v[16:31]
	v_exp_f32_e32 v61, v79
	v_exp_f32_e32 v95, v80
	v_exp_f32_e32 v81, v81
	ds_read_b128 v[152:155], v140 offset:24576
	ds_read_b128 v[156:159], v140 offset:28672
	s_waitcnt lgkmcnt(4)
	v_mfma_f32_32x32x16_bf16 v[0:15], v[40:43], v[56:59], v[0:15]
	v_exp_f32_e32 v82, v82
	v_exp_f32_e32 v83, v83
	v_add_f32_e32 v78, v82, v60
	v_add_f32_e32 v79, v83, v61
	s_waitcnt lgkmcnt(2)
	v_mfma_f32_32x32x16_bf16 v[0:15], v[120:123], v[48:51], v[0:15]
	ds_read_b128 v[56:59], v139 offset:24576
	ds_read_b128 v[160:163], v139 offset:28672
	ds_read_b128 v[40:43], v164 offset:16384
	ds_read_b128 v[32:35], v164 offset:20480
	v_cvt_pk_bf16_f32 v82, v82, v83
	v_exp_f32_e32 v151, v62
	v_exp_f32_e32 v64, v64
	v_exp_f32_e32 v65, v65
	v_mfma_f32_32x32x16_bf16 v[16:31], v[44:47], v[48:51], v[16:31]
	v_exp_f32_e32 v44, v84
	v_exp_f32_e32 v45, v85
	v_exp_f32_e32 v84, v86
	v_exp_f32_e32 v85, v87
	v_add_f32_e32 v46, v44, v95
	v_add_f32_e32 v47, v45, v81
	v_add_f32_e32 v48, v84, v78
	s_waitcnt lgkmcnt(4)
	v_mfma_f32_32x32x16_bf16 v[0:15], v[156:159], v[52:55], v[0:15]
	v_add_f32_e32 v49, v85, v79
	v_exp_f32_e32 v78, v88
	v_exp_f32_e32 v79, v89
	v_exp_f32_e32 v87, v92
	v_cvt_pk_bf16_f32 v83, v44, v45
	v_exp_f32_e32 v44, v90
	v_mfma_f32_32x32x16_bf16 v[16:31], v[152:155], v[52:55], v[16:31]
	v_exp_f32_e32 v45, v91
	v_exp_f32_e32 v92, v93
	v_add_f32_e32 v46, v78, v46
	v_add_f32_e32 v47, v79, v47
	ds_read_b128 v[124:127], v165 offset:16384
	ds_read_b128 v[120:123], v165 offset:20480
	s_waitcnt lgkmcnt(4)
	v_mfma_f32_32x32x16_bf16 v[0:15], v[160:163], v[36:39], v[0:15]
	v_exp_f32_e32 v160, v63
	v_cvt_pk_bf16_f32 v80, v60, v61
	v_cvt_pk_bf16_f32 v81, v95, v81
	v_add_f32_e32 v48, v44, v48
	v_add_f32_e32 v49, v45, v49
	v_add_f32_e32 v46, v87, v46
	v_add_f32_e32 v47, v92, v47
	v_mfma_f32_32x32x16_bf16 v[16:31], v[56:59], v[36:39], v[16:31]
	v_add_f32_e32 v161, v151, v48
	v_add_f32_e32 v162, v160, v49
	v_cvt_pk_bf16_f32 v84, v84, v85
	v_cvt_pk_bf16_f32 v85, v78, v79
	v_cvt_pk_bf16_f32 v86, v44, v45
	v_add_f32_e32 v78, v64, v46
	v_add_f32_e32 v79, v65, v47
	s_waitcnt lgkmcnt(3)
	v_mfma_f32_32x32x16_bf16 v[48:63], v[40:43], v[96:99], 0
	ds_read_b128 v[88:91], v166 offset:16384
	ds_read_b128 v[152:155], v166 offset:20480
	v_exp_f32_e32 v66, v66
	v_exp_f32_e32 v67, v67
	v_exp_f32_e32 v68, v68
	v_exp_f32_e32 v69, v69
	v_cvt_pk_bf16_f32 v87, v87, v92
	s_waitcnt lgkmcnt(4)
	v_mfma_f32_32x32x16_bf16 v[32:47], v[32:35], v[96:99], 0
	ds_read_b128 v[156:159], v94 offset:16384
	ds_read_b128 v[92:95], v94 offset:20480
	v_add_f32_e32 v161, v66, v161
	v_add_f32_e32 v162, v67, v162
	v_add_f32_e32 v78, v68, v78
	v_add_f32_e32 v79, v69, v79
	s_waitcnt lgkmcnt(5)
	v_mfma_f32_32x32x16_bf16 v[48:63], v[124:127], v[100:103], v[48:63]
	v_exp_f32_e32 v70, v70
	v_exp_f32_e32 v71, v71
	s_add_i32 s9, s3, 2
	s_add_i32 s3, s3, -2
	v_lshl_add_u64 v[136:137], v[136:137], 0, s[22:23]
	s_waitcnt lgkmcnt(4)
	v_mfma_f32_32x32x16_bf16 v[32:47], v[120:123], v[100:103], v[32:47]
	v_add_f32_e32 v120, v70, v161
	v_add_f32_e32 v121, v71, v162
	s_cmp_lt_u32 s3, s2
	s_mov_b32 s3, s9
	s_waitcnt lgkmcnt(3)
	v_mfma_f32_32x32x16_bf16 v[48:63], v[88:91], v[104:107], v[48:63]
	v_cvt_pk_bf16_f32 v91, v68, v69
	v_exp_f32_e32 v68, v72
	v_exp_f32_e32 v69, v73
	v_exp_f32_e32 v72, v74
	v_exp_f32_e32 v73, v75
	v_exp_f32_e32 v74, v76
	v_exp_f32_e32 v75, v77
	s_waitcnt lgkmcnt(2)
	v_mfma_f32_32x32x16_bf16 v[32:47], v[152:155], v[104:107], v[32:47]
	v_cvt_pk_bf16_f32 v88, v151, v160
	v_cvt_pk_bf16_f32 v89, v64, v65
	v_cvt_pk_bf16_f32 v90, v66, v67
	v_add_f32_e32 v65, v68, v78
	v_add_f32_e32 v67, v69, v79
	s_waitcnt lgkmcnt(1)
	v_mfma_f32_32x32x16_bf16 v[48:63], v[156:159], v[108:111], v[48:63]
	v_add_f32_e32 v64, v72, v120
	v_add_f32_e32 v66, v73, v121
	v_add_f32_e32 v65, v74, v65
	v_add_f32_e32 v67, v75, v67
	s_waitcnt lgkmcnt(0)
	v_mfma_f32_32x32x16_bf16 v[32:47], v[92:95], v[108:111], v[32:47]
	v_cvt_pk_bf16_f32 v92, v70, v71
	v_cvt_pk_bf16_f32 v93, v68, v69
	v_cvt_pk_bf16_f32 v94, v72, v73
	v_cvt_pk_bf16_f32 v95, v74, v75
	v_add_f32_e64 v64, v64, v66
	v_add_f32_e64 v65, v65, v67
	s_waitcnt lgkmcnt(0)
	s_barrier
	v_add_f32_e32 v64, v64, v65
	v_add_f32_e32 v150, v150, v64
	s_cbranch_scc1 .LBB0_898
	v_ashrrev_i32_e32 v64, 1, v129
	v_and_or_b32 v132, v64, s88, v148
	v_mov_b64_e32 v[64:65], s[12:13]
	v_mad_i64_i32 v[64:65], s[2:3], v132, s33, v[64:65]
	v_lshlrev_b32_e32 v176, 4, v138
	s_waitcnt vmcnt(1)
	ds_write_b128 v142, v[112:115] offset:16384
	s_waitcnt vmcnt(0)
	ds_write_b128 v142, v[116:119] offset:24576
	v_lshl_add_u64 v[64:65], v[64:65], 0, v[176:177]
	global_load_dwordx4 v[124:127], v[64:65], off offset:2560
	global_load_dwordx4 v[120:123], v[64:65], off offset:2592
	global_load_dwordx4 v[116:119], v[64:65], off offset:2624
	global_load_dwordx4 v[112:115], v[64:65], off offset:2656
	v_mov_b64_e32 v[64:65], s[14:15]
	v_mad_i64_i32 v[64:65], s[2:3], v132, s33, v[64:65]
	v_and_b32_e32 v66, 16, v131
	v_mov_b32_e32 v67, v177
	v_lshl_add_u64 v[64:65], v[64:65], 0, v[66:67]
	global_load_dwordx4 v[96:99], v[64:65], off offset:1024
	global_load_dwordx4 v[100:103], v[64:65], off offset:1056
	global_load_dwordx4 v[104:107], v[64:65], off offset:1088
	global_load_dwordx4 v[108:111], v[64:65], off offset:1120
	v_lshl_add_u64 v[64:65], s[34:35], 0, v[134:135]
	v_lshlrev_b32_e32 v76, 1, v130
	v_mov_b32_e32 v77, v177
	v_lshl_add_u64 v[72:73], v[64:65], 0, v[76:77]
	s_mov_b32 s2, 0x48000
	v_add_co_u32_e32 v68, vcc, s2, v72
	s_mov_b32 s2, 0x90000
	s_nop 0
	v_addc_co_u32_e32 v69, vcc, 0, v73, vcc
	global_load_dwordx4 v[64:67], v[72:73], off offset:2048
	v_ashrrev_i32_e32 v133, 31, v132
	global_load_dwordx4 v[68:71], v[68:69], off offset:2048
	v_add_co_u32_e32 v72, vcc, s2, v72
	v_mad_i64_i32 v[78:79], s[2:3], s8, v128, 0
	v_lshl_add_u64 v[78:79], v[78:79], 1, s[10:11]
	v_addc_co_u32_e32 v73, vcc, 0, v73, vcc
	v_lshl_add_u64 v[76:77], v[78:79], 0, v[76:77]
	global_load_dwordx4 v[72:75], v[72:73], off offset:2048
	s_nop 0
	global_load_dwordx4 v[76:79], v[76:77], off
	ds_read_b128 v[128:131], v144 offset:8192
	ds_read_b128 v[134:137], v144 offset:12288
	ds_read_b128 v[146:149], v141 offset:8192
	ds_read_b128 v[152:155], v141 offset:12288
	v_exp_f32_e32 v138, v48
	v_exp_f32_e32 v142, v49
	s_waitcnt lgkmcnt(3)
	v_mfma_f32_32x32x16_bf16 v[16:31], v[128:131], v[80:83], v[16:31]
	v_exp_f32_e32 v151, v50
	v_add_f32_e32 v143, 0, v138
	v_add_f32_e32 v145, 0, v142
	v_exp_f32_e32 v156, v51
	ds_read_b128 v[48:51], v140 offset:8192
	ds_read_b128 v[128:131], v140 offset:12288
	v_exp_f32_e32 v52, v52
	s_waitcnt lgkmcnt(4)
	v_mfma_f32_32x32x16_bf16 v[0:15], v[134:137], v[80:83], v[0:15]
	v_exp_f32_e32 v53, v53
	v_exp_f32_e32 v54, v54
	v_exp_f32_e32 v55, v55
	v_add_f32_e32 v157, 0, v151
	v_add_f32_e32 v158, 0, v156
	v_add_f32_e32 v143, v52, v143
	s_waitcnt lgkmcnt(3)
	v_mfma_f32_32x32x16_bf16 v[16:31], v[146:149], v[84:87], v[16:31]
	v_add_f32_e32 v145, v53, v145
	v_add_f32_e32 v146, v54, v157
	ds_read_b128 v[80:83], v139 offset:8192
	ds_read_b128 v[134:137], v139 offset:12288
	v_exp_f32_e32 v56, v56
	v_exp_f32_e32 v57, v57
	v_exp_f32_e32 v58, v58
	s_waitcnt lgkmcnt(4)
	v_mfma_f32_32x32x16_bf16 v[0:15], v[152:155], v[84:87], v[0:15]
	v_add_f32_e32 v84, v55, v158
	v_exp_f32_e32 v59, v59
	v_exp_f32_e32 v60, v60
	v_exp_f32_e32 v32, v32
	v_exp_f32_e32 v33, v33
	v_exp_f32_e32 v34, v34
	s_waitcnt lgkmcnt(3)
	v_mfma_f32_32x32x16_bf16 v[16:31], v[48:51], v[88:91], v[16:31]
	v_cvt_pk_bf16_f32 v51, v54, v55
	v_exp_f32_e32 v54, v61
	v_exp_f32_e32 v55, v62
	v_exp_f32_e32 v61, v63
	v_exp_f32_e32 v35, v35
	v_add_f32_e32 v85, v56, v143
	v_add_f32_e32 v86, v57, v145
	v_add_f32_e32 v87, v58, v146
	v_add_f32_e32 v84, v59, v84
	v_cvt_pk_bf16_f32 v48, v138, v142
	v_cvt_pk_bf16_f32 v49, v151, v156
	v_cvt_pk_bf16_f32 v50, v52, v53
	v_add_f32_e32 v52, v60, v85
	v_add_f32_e32 v53, v54, v86
	v_add_f32_e32 v62, v55, v87
	v_add_f32_e32 v63, v61, v84
	v_exp_f32_e32 v36, v36
	v_exp_f32_e32 v37, v37
	v_exp_f32_e32 v38, v38
	v_exp_f32_e32 v39, v39
	s_waitcnt lgkmcnt(1)
	v_mfma_f32_32x32x16_bf16 v[16:31], v[80:83], v[92:95], v[16:31]
	v_add_f32_e32 v80, v32, v52
	v_add_f32_e32 v81, v33, v53
	v_cvt_pk_bf16_f32 v52, v56, v57
	v_cvt_pk_bf16_f32 v53, v58, v59
	v_cvt_pk_bf16_f32 v54, v60, v54
	v_cvt_pk_bf16_f32 v55, v55, v61
	v_add_f32_e32 v56, v34, v62
	v_add_f32_e32 v57, v35, v63
	v_exp_f32_e32 v40, v40
	v_add_f32_e32 v58, v36, v80
	v_add_f32_e32 v59, v37, v81
	v_add_f32_e32 v56, v38, v56
	v_exp_f32_e32 v41, v41
	v_add_f32_e32 v57, v39, v57
	v_mfma_f32_32x32x16_bf16 v[0:15], v[128:131], v[88:91], v[0:15]
	v_cvt_pk_bf16_f32 v32, v32, v33
	v_cvt_pk_bf16_f32 v33, v34, v35
	v_cvt_pk_bf16_f32 v34, v36, v37
	v_exp_f32_e32 v37, v42
	v_cvt_pk_bf16_f32 v35, v38, v39
	v_exp_f32_e32 v38, v43
	v_exp_f32_e32 v39, v44
	v_exp_f32_e32 v43, v45
	v_exp_f32_e32 v44, v46
	v_exp_f32_e32 v45, v47
	v_add_f32_e32 v58, v40, v58
	v_add_f32_e32 v59, v41, v59
	v_add_f32_e32 v36, v37, v56
	v_add_f32_e32 v42, v38, v57
	v_add_f32_e32 v56, v39, v58
	v_add_f32_e32 v58, v43, v59
	s_waitcnt lgkmcnt(0)
	v_mfma_f32_32x32x16_bf16 v[0:15], v[134:137], v[92:95], v[0:15]
	v_add_f32_e32 v57, v44, v36
	v_add_f32_e32 v59, v45, v42
	v_cvt_pk_bf16_f32 v36, v40, v41
	v_cvt_pk_bf16_f32 v37, v37, v38
	v_cvt_pk_bf16_f32 v38, v39, v43
	v_cvt_pk_bf16_f32 v39, v44, v45
	s_waitcnt lgkmcnt(0)
	s_barrier
	ds_read_b128 v[40:43], v144 offset:24576
	ds_read_b128 v[44:47], v144 offset:28672
	s_waitcnt lgkmcnt(1)
	v_mfma_f32_32x32x16_bf16 v[16:31], v[40:43], v[48:51], v[16:31]
	s_waitcnt lgkmcnt(0)
	v_mfma_f32_32x32x16_bf16 v[0:15], v[44:47], v[48:51], v[0:15]
	ds_read_b128 v[40:43], v141 offset:24576
	ds_read_b128 v[44:47], v141 offset:28672
	s_waitcnt lgkmcnt(1)
	v_mfma_f32_32x32x16_bf16 v[16:31], v[40:43], v[52:55], v[16:31]
	s_waitcnt lgkmcnt(0)
	v_mfma_f32_32x32x16_bf16 v[0:15], v[44:47], v[52:55], v[0:15]
	ds_read_b128 v[40:43], v140 offset:24576
	ds_read_b128 v[44:47], v140 offset:28672
	s_waitcnt lgkmcnt(1)
	v_mfma_f32_32x32x16_bf16 v[16:31], v[40:43], v[32:35], v[16:31]
	s_waitcnt lgkmcnt(0)
	v_mfma_f32_32x32x16_bf16 v[0:15], v[44:47], v[32:35], v[0:15]
	ds_read_b128 v[32:35], v139 offset:24576
	ds_read_b128 v[40:43], v139 offset:28672
	s_waitcnt lgkmcnt(1)
	v_mfma_f32_32x32x16_bf16 v[16:31], v[32:35], v[36:39], v[16:31]
	v_add_f32_e64 v32, v56, v58
	v_add_f32_e64 v33, v57, v59
	v_add_f32_e32 v32, v32, v33
	v_add_f32_e32 v32, v150, v32
	v_mov_b32_e32 v33, v32
	s_nop 1
	v_permlane32_swap_b32_e32 v32, v33
	v_add_f32_e32 v32, v32, v33
	v_div_scale_f32 v33, s[2:3], v32, v32, 1.0
	v_rcp_f32_e32 v34, v33
	s_waitcnt lgkmcnt(0)
	v_mfma_f32_32x32x16_bf16 v[0:15], v[40:43], v[36:39], v[0:15]
	s_waitcnt vmcnt(11)
	v_mov_b32_e32 v40, v127
	s_nop 1
	v_permlane32_swap_b32_e32 v125, v40
	v_fma_f32 v35, -v33, v34, 1.0
	v_fmac_f32_e32 v34, v35, v34
	v_div_scale_f32 v35, vcc, 1.0, v32, 1.0
	v_mul_f32_e32 v36, v35, v34
	v_fma_f32 v37, -v33, v36, v35
	v_fmac_f32_e32 v36, v37, v34
	v_fma_f32 v33, -v33, v36, v35
	v_div_fmas_f32 v33, v33, v34, v36
	v_mov_b32_e32 v35, v126
	v_div_fixup_f32 v34, v33, v32, 1.0
	s_nop 0
	v_permlane32_swap_b32_e32 v124, v35
	v_lshlrev_b32_e32 v38, 16, v124
	v_and_b32_e32 v39, 0xffff0000, v124
	v_mul_f32_e32 v16, v16, v34
	v_mul_f32_e32 v17, v17, v34
	v_mul_f32_e32 v18, v18, v34
	v_mul_f32_e32 v19, v19, v34
	v_mul_f32_e32 v16, v16, v38
	v_mul_f32_e32 v17, v17, v39
	v_lshlrev_b32_e32 v38, 16, v125
	v_and_b32_e32 v39, 0xffff0000, v125
	v_mul_f32_e32 v18, v18, v38
	v_mul_f32_e32 v19, v19, v39
	v_cvt_pk_bf16_f32 v16, v16, v17
	v_cvt_pk_bf16_f32 v17, v18, v19
	v_lshlrev_b32_e32 v18, 16, v35
	v_and_b32_e32 v19, 0xffff0000, v35
	v_mul_f32_e32 v20, v20, v34
	v_mul_f32_e32 v21, v21, v34
	v_mul_f32_e32 v22, v22, v34
	v_mul_f32_e32 v23, v23, v34
	v_mul_f32_e32 v18, v20, v18
	v_mul_f32_e32 v19, v21, v19
	v_lshlrev_b32_e32 v20, 16, v40
	v_and_b32_e32 v21, 0xffff0000, v40
	v_lshlrev_b64 v[32:33], 11, v[132:133]
	v_mul_f32_e32 v20, v22, v20
	v_mul_f32_e32 v21, v23, v21
	v_lshl_add_u64 v[32:33], s[6:7], 0, v[32:33]
	v_cvt_pk_bf16_f32 v18, v18, v19
	v_cvt_pk_bf16_f32 v19, v20, v21
	s_waitcnt vmcnt(10)
	v_mov_b32_e32 v22, v122
	v_lshl_add_u64 v[36:37], v[32:33], 0, v[176:177]
	v_permlane32_swap_b32_e32 v16, v18
	v_permlane32_swap_b32_e32 v17, v19
	v_permlane32_swap_b32_e32 v120, v22
	v_mov_b32_e32 v23, v123
	global_store_dwordx4 v[36:37], v[16:19], off offset:512
	s_nop 0
	v_permlane32_swap_b32_e32 v121, v23
	v_lshlrev_b32_e32 v16, 16, v120
	v_and_b32_e32 v17, 0xffff0000, v120
	v_mul_f32_e32 v18, v24, v34
	v_mul_f32_e32 v19, v25, v34
	v_mul_f32_e32 v20, v26, v34
	v_mul_f32_e32 v21, v27, v34
	v_mul_f32_e32 v16, v18, v16
	v_mul_f32_e32 v17, v19, v17
	v_lshlrev_b32_e32 v18, 16, v121
	v_and_b32_e32 v19, 0xffff0000, v121
	v_mul_f32_e32 v18, v20, v18
	v_mul_f32_e32 v19, v21, v19
	v_cvt_pk_bf16_f32 v16, v16, v17
	v_cvt_pk_bf16_f32 v17, v18, v19
	v_lshlrev_b32_e32 v18, 16, v22
	v_and_b32_e32 v19, 0xffff0000, v22
	v_mul_f32_e32 v20, v28, v34
	v_mul_f32_e32 v21, v29, v34
	v_mul_f32_e32 v0, v0, v34
	v_mul_f32_e32 v1, v1, v34
	v_mul_f32_e32 v18, v20, v18
	v_mul_f32_e32 v19, v21, v19
	v_lshlrev_b32_e32 v20, 16, v23
	v_and_b32_e32 v21, 0xffff0000, v23
	v_mul_f32_e32 v22, v30, v34
	v_mul_f32_e32 v23, v31, v34
	v_cvt_pk_bf16_f32 v18, v18, v19
	v_mul_f32_e32 v20, v22, v20
	v_mul_f32_e32 v21, v23, v21
	s_nop 0
	v_permlane32_swap_b32_e32 v16, v18
	v_cvt_pk_bf16_f32 v19, v20, v21
	s_nop 1
	v_permlane32_swap_b32_e32 v17, v19
	global_store_dwordx4 v[36:37], v[16:19], off offset:544
	v_mul_f32_e32 v2, v2, v34
	v_mul_f32_e32 v3, v3, v34
	v_mul_f32_e32 v4, v4, v34
	v_mul_f32_e32 v5, v5, v34
	s_waitcnt vmcnt(11)
	v_mov_b32_e32 v18, v118
	s_nop 1
	v_permlane32_swap_b32_e32 v116, v18
	v_mov_b32_e32 v19, v119
	s_nop 1
	v_permlane32_swap_b32_e32 v117, v19
	v_lshlrev_b32_e32 v16, 16, v116
	v_and_b32_e32 v17, 0xffff0000, v116
	v_mul_f32_e32 v0, v0, v16
	v_mul_f32_e32 v1, v1, v17
	v_lshlrev_b32_e32 v16, 16, v117
	v_and_b32_e32 v17, 0xffff0000, v117
	v_mul_f32_e32 v2, v2, v16
	v_mul_f32_e32 v3, v3, v17
	v_cvt_pk_bf16_f32 v0, v0, v1
	v_cvt_pk_bf16_f32 v1, v2, v3
	v_lshlrev_b32_e32 v2, 16, v18
	v_and_b32_e32 v3, 0xffff0000, v18
	v_mul_f32_e32 v2, v4, v2
	v_mul_f32_e32 v3, v5, v3
	v_lshlrev_b32_e32 v4, 16, v19
	v_and_b32_e32 v5, 0xffff0000, v19
	v_mul_f32_e32 v6, v6, v34
	v_mul_f32_e32 v7, v7, v34
	v_cvt_pk_bf16_f32 v2, v2, v3
	v_mul_f32_e32 v4, v6, v4
	v_mul_f32_e32 v5, v7, v5
	s_waitcnt vmcnt(10)
	v_mov_b32_e32 v6, v114
	v_cvt_pk_bf16_f32 v3, v4, v5
	v_permlane32_swap_b32_e32 v0, v2
	s_nop 0
	v_permlane32_swap_b32_e32 v1, v3
	v_permlane32_swap_b32_e32 v112, v6
	v_mov_b32_e32 v7, v115
	global_store_dwordx4 v[36:37], v[0:3], off offset:576
	s_nop 0
	v_permlane32_swap_b32_e32 v113, v7
	v_lshlrev_b32_e32 v0, 16, v112
	v_and_b32_e32 v1, 0xffff0000, v112
	v_mul_f32_e32 v2, v8, v34
	v_mul_f32_e32 v3, v9, v34
	v_mul_f32_e32 v4, v10, v34
	v_mul_f32_e32 v5, v11, v34
	v_mul_f32_e32 v0, v2, v0
	v_mul_f32_e32 v1, v3, v1
	v_lshlrev_b32_e32 v2, 16, v113
	v_and_b32_e32 v3, 0xffff0000, v113
	v_mul_f32_e32 v2, v4, v2
	v_mul_f32_e32 v3, v5, v3
	v_cvt_pk_bf16_f32 v0, v0, v1
	v_cvt_pk_bf16_f32 v1, v2, v3
	v_lshlrev_b32_e32 v2, 16, v6
	v_and_b32_e32 v3, 0xffff0000, v6
	v_mul_f32_e32 v4, v12, v34
	v_mul_f32_e32 v5, v13, v34
	s_mov_b64 s[2:3], 0x200
	v_mul_f32_e32 v2, v4, v2
	v_mul_f32_e32 v3, v5, v3
	v_lshlrev_b32_e32 v4, 16, v7
	v_and_b32_e32 v5, 0xffff0000, v7
	v_mul_f32_e32 v6, v14, v34
	v_mul_f32_e32 v7, v15, v34
	v_cvt_pk_bf16_f32 v2, v2, v3
	v_mul_f32_e32 v4, v6, v4
	v_mul_f32_e32 v5, v7, v5
	v_lshl_add_u64 v[32:33], v[36:37], 0, s[2:3]
	v_cvt_pk_bf16_f32 v3, v4, v5
	v_permlane32_swap_b32_e32 v0, v2
	s_nop 0
	v_permlane32_swap_b32_e32 v1, v3
	s_branch .LBB0_876
